# attention softmax: scalar two-chain row sum instead of packed adds (packed f32 VALU is slow beside the partner wave's MFMAs)
# speedup vs baseline: 1.0195x; 1.0071x over previous
; __device__ __forceinline__ void attn_phase(const Args& a, int layer, LAS unsigned char* lds, int G, int need_ctx) {
;     ...
;             float mx = sc[0];
; #pragma unroll
;             for (int t = 1; t < 16; ++t) mx = fmaxf(mx, sc[t]);
;             mx = fmaxf(mx, __shfl_xor(mx, 32));
;             const float m_new = fmaxf(m_run, mx), alpha = __expf(m_run - m_new);
;             float rs = 0.f;
; #pragma unroll
;             for (int t = 0; t < 16; ++t) { sc[t] = __expf(sc[t] - m_new); rs += sc[t]; }
;             rs += __shfl_xor(rs, 32);
;             l_run = l_run * alpha + rs; m_run = m_new;
.LBB0_196:
	s_nop 8
	v_max3_f32 v80, v64, v65, v66
	v_max3_f32 v81, v67, v68, v69
	v_max3_f32 v82, v70, v71, v72
	v_max3_f32 v83, v73, v74, v75
	v_max3_f32 v84, v76, v77, v78
	v_max3_f32 v80, v80, v81, v82
	v_max3_f32 v83, v83, v84, v79
	v_max_f32_e32 v80, v80, v83
	ds_bpermute_b32 v81, v235, v80
	s_add_i32 s23, s23, 32
	v_add_u32_e32 v236, 0x7c, v236
	s_mov_b32 s12, 0x3fb8aa3b
	s_waitcnt lgkmcnt(0)
	v_max_f32_e32 v80, v80, v81
	v_max_f32_e32 v81, v238, v80
	v_sub_f32_e32 v82, v81, v238
	v_cmp_lt_f32_e32 vcc, 0x40a00000, v82
	s_nop 1
	v_cndmask_b32_e32 v80, v238, v81, vcc
	v_mul_f32_e32 v83, s12, v80
	v_sub_f32_e32 v84, v238, v80
	v_mul_f32_e32 v87, s12, v80
	v_mul_f32_e32 v84, s12, v84
	v_fma_f32 v64, v64, s12, -v87
	v_fma_f32 v65, v65, s12, -v87
	v_exp_f32_e32 v86, v84
	v_exp_f32_e32 v64, v64
	v_fma_f32 v66, v66, s12, -v87
	v_mov_b32_e32 v238, v80
	v_exp_f32_e32 v65, v65
	v_fma_f32 v67, v67, s12, -v87
	v_add_f32_e32 v88, v64, v65
	v_exp_f32_e32 v66, v66
	v_fma_f32 v68, v68, s12, -v87
	v_cvt_pk_bf16_f32 v80, v64, v65
	v_exp_f32_e32 v67, v67
	v_fma_f32 v69, v69, s12, -v87
	v_add_f32_e32 v89, v66, v67
	v_exp_f32_e32 v68, v68
	v_fma_f32 v70, v70, s12, -v87
	v_cvt_pk_bf16_f32 v81, v66, v67
	v_add_f32_e32 v88, v88, v68
	v_exp_f32_e32 v69, v69
	v_fma_f32 v71, v71, s12, -v87
	v_add_f32_e32 v89, v89, v69
	v_exp_f32_e32 v70, v70
	v_fma_f32 v72, v72, s12, -v87
	v_cvt_pk_bf16_f32 v82, v68, v69
	v_add_f32_e32 v88, v88, v70
	v_exp_f32_e32 v71, v71
	v_fma_f32 v73, v73, s12, -v87
	v_add_f32_e32 v89, v89, v71
	v_exp_f32_e32 v72, v72
	v_fma_f32 v74, v74, s12, -v87
	v_cvt_pk_bf16_f32 v83, v70, v71
	v_add_f32_e32 v88, v88, v72
	v_exp_f32_e32 v73, v73
	v_fma_f32 v75, v75, s12, -v87
	v_add_f32_e32 v89, v89, v73
	v_exp_f32_e32 v74, v74
	v_fma_f32 v76, v76, s12, -v87
	v_cvt_pk_bf16_f32 v92, v72, v73
	v_add_f32_e32 v88, v88, v74
	v_exp_f32_e32 v75, v75
	v_fma_f32 v77, v77, s12, -v87
	v_add_f32_e32 v89, v89, v75
	v_exp_f32_e32 v76, v76
	v_fma_f32 v78, v78, s12, -v87
	v_cvt_pk_bf16_f32 v93, v74, v75
	v_add_f32_e32 v88, v88, v76
	v_exp_f32_e32 v77, v77
	v_fma_f32 v79, v79, s12, -v87
	v_add_f32_e32 v89, v89, v77
	v_exp_f32_e32 v78, v78
	v_cvt_pk_bf16_f32 v94, v76, v77
	v_add_f32_e32 v88, v88, v78
	v_exp_f32_e32 v79, v79
	s_nop 0
	v_add_f32_e32 v89, v89, v79
	v_cvt_pk_bf16_f32 v95, v78, v79
	v_add_f32_e32 v88, v88, v89
	v_fma_f32 v237, v237, v86, v88
	s_and_b64 vcc, exec, vcc
	s_cbranch_vccz .Latt_norescale
	v_pk_mul_f32 v[62:63], v[62:63], v[86:87] op_sel_hi:[1,0]
	v_pk_mul_f32 v[60:61], v[60:61], v[86:87] op_sel_hi:[1,0]
	v_pk_mul_f32 v[58:59], v[58:59], v[86:87] op_sel_hi:[1,0]
	v_pk_mul_f32 v[56:57], v[56:57], v[86:87] op_sel_hi:[1,0]
	v_pk_mul_f32 v[54:55], v[54:55], v[86:87] op_sel_hi:[1,0]
	v_pk_mul_f32 v[52:53], v[52:53], v[86:87] op_sel_hi:[1,0]
	v_pk_mul_f32 v[50:51], v[50:51], v[86:87] op_sel_hi:[1,0]
	v_pk_mul_f32 v[48:49], v[48:49], v[86:87] op_sel_hi:[1,0]
	v_pk_mul_f32 v[46:47], v[46:47], v[86:87] op_sel_hi:[1,0]
	v_pk_mul_f32 v[44:45], v[44:45], v[86:87] op_sel_hi:[1,0]
	v_pk_mul_f32 v[42:43], v[42:43], v[86:87] op_sel_hi:[1,0]
	v_pk_mul_f32 v[40:41], v[40:41], v[86:87] op_sel_hi:[1,0]
	v_pk_mul_f32 v[38:39], v[38:39], v[86:87] op_sel_hi:[1,0]
	v_pk_mul_f32 v[36:37], v[36:37], v[86:87] op_sel_hi:[1,0]
	v_pk_mul_f32 v[34:35], v[34:35], v[86:87] op_sel_hi:[1,0]
	v_pk_mul_f32 v[32:33], v[32:33], v[86:87] op_sel_hi:[1,0]
	v_pk_mul_f32 v[30:31], v[30:31], v[86:87] op_sel_hi:[1,0]
	v_pk_mul_f32 v[28:29], v[28:29], v[86:87] op_sel_hi:[1,0]
	v_pk_mul_f32 v[26:27], v[26:27], v[86:87] op_sel_hi:[1,0]
	v_pk_mul_f32 v[24:25], v[24:25], v[86:87] op_sel_hi:[1,0]
	v_pk_mul_f32 v[22:23], v[22:23], v[86:87] op_sel_hi:[1,0]
	v_pk_mul_f32 v[20:21], v[20:21], v[86:87] op_sel_hi:[1,0]
	v_pk_mul_f32 v[18:19], v[18:19], v[86:87] op_sel_hi:[1,0]
	v_pk_mul_f32 v[16:17], v[16:17], v[86:87] op_sel_hi:[1,0]
	v_pk_mul_f32 v[14:15], v[14:15], v[86:87] op_sel_hi:[1,0]
	v_pk_mul_f32 v[12:13], v[12:13], v[86:87] op_sel_hi:[1,0]
	v_pk_mul_f32 v[10:11], v[10:11], v[86:87] op_sel_hi:[1,0]
	v_pk_mul_f32 v[8:9], v[8:9], v[86:87] op_sel_hi:[1,0]
	v_pk_mul_f32 v[6:7], v[6:7], v[86:87] op_sel_hi:[1,0]
	v_pk_mul_f32 v[4:5], v[4:5], v[86:87] op_sel_hi:[1,0]
	v_pk_mul_f32 v[2:3], v[2:3], v[86:87] op_sel_hi:[1,0]
	v_pk_mul_f32 v[0:1], v[0:1], v[86:87] op_sel_hi:[1,0]
